# stack: static gMLP chunk per workgroup, top-counter grid barrier, rebalanced P2 spare work, nt on fp8-epilogue gate stores and on P0/P1-queue weight reads, on top of p1loop+p1nt+tailnt+gmlpnt
# speedup vs baseline: 1.0108x; 1.0108x over previous
.LBB0_17:
	v_add_u32_e32 v28, s2, v1
	v_lshlrev_b64 v[8:9], 2, v[28:29]
	v_mad_u64_u32 v[6:7], s[4:5], v28, s3, v[30:31]
	v_add_u32_e32 v2, 8, v28
	v_add_u32_e32 v4, 16, v28
	v_add_u32_e32 v28, 24, v28
	v_lshl_add_u64 v[10:11], s[50:51], 0, v[8:9]
	v_mov_b32_e32 v3, v29
	v_mov_b32_e32 v5, v29
	v_lshl_add_u64 v[12:13], s[64:65], 0, v[8:9]
	v_lshl_add_u64 v[42:43], s[66:67], 0, v[8:9]
	v_lshl_add_u64 v[44:45], s[68:69], 0, v[8:9]
	v_lshl_add_u64 v[8:9], s[54:55], 0, v[8:9]
	v_lshlrev_b64 v[50:51], 2, v[28:29]
	global_load_dwordx4 v[14:17], v[6:7], off nt
	v_mad_u64_u32 v[52:53], s[4:5], v28, s3, v[30:31]
	global_load_dword v28, v[10:11], off
	global_load_dword v62, v[12:13], off
	global_load_dword v63, v[42:43], off
	global_load_dword v64, v[44:45], off
	global_load_dword v65, v[8:9], off
	global_load_dword v66, v[10:11], off offset:32
	global_load_dword v67, v[8:9], off offset:32
	global_load_dword v68, v[10:11], off offset:64
	global_load_dword v69, v[8:9], off offset:64
	global_load_dword v70, v[10:11], off offset:96
	global_load_dword v71, v[8:9], off offset:96
	v_lshlrev_b64 v[46:47], 2, v[2:3]
	v_lshlrev_b64 v[48:49], 2, v[4:5]
	v_mad_u64_u32 v[2:3], s[4:5], v2, s3, v[30:31]
	v_mad_u64_u32 v[4:5], s[4:5], v4, s3, v[30:31]
	v_lshl_add_u64 v[54:55], s[64:65], 0, v[46:47]
	v_lshl_add_u64 v[56:57], s[66:67], 0, v[46:47]
	v_lshl_add_u64 v[46:47], s[68:69], 0, v[46:47]
	v_lshl_add_u64 v[58:59], s[64:65], 0, v[48:49]
	v_lshl_add_u64 v[60:61], s[66:67], 0, v[48:49]
	v_lshl_add_u64 v[48:49], s[68:69], 0, v[48:49]
	v_lshl_add_u64 v[42:43], s[64:65], 0, v[50:51]
	v_lshl_add_u64 v[44:45], s[66:67], 0, v[50:51]
	v_lshl_add_u64 v[50:51], s[68:69], 0, v[50:51]
	global_load_dwordx4 v[10:13], v[2:3], off nt
	global_load_dwordx4 v[6:9], v[4:5], off nt
	s_nop 0
	global_load_dwordx4 v[2:5], v[52:53], off nt
	s_nop 0
	global_load_dword v52, v[54:55], off
	global_load_dword v53, v[56:57], off
	s_nop 0
	global_load_dword v46, v[46:47], off
	s_nop 0
	global_load_dword v47, v[58:59], off
	global_load_dword v54, v[60:61], off
	s_nop 0
	global_load_dword v48, v[48:49], off
	s_nop 0
	global_load_dword v42, v[42:43], off
	s_nop 0
	global_load_dword v43, v[44:45], off
	s_nop 0
	global_load_dword v44, v[50:51], off
	s_add_i32 s2, s2, 32
	s_cmpk_eq_i32 s2, 0x80
	s_waitcnt vmcnt(22)
	v_mul_f32_e32 v45, 0xbfb8aa3b, v28
	s_waitcnt vmcnt(21)
	v_mul_f32_e32 v49, 0xbfb8aa3b, v62
	v_exp_f32_e32 v45, v45
	s_waitcnt vmcnt(20)
	v_mul_f32_e32 v50, 0xbfb8aa3b, v63
	v_exp_f32_e32 v49, v49
	s_waitcnt vmcnt(17)
	v_mul_f32_e32 v56, 0xbfb8aa3b, v66
	s_waitcnt vmcnt(16)
	v_mul_f32_e32 v57, 0xbfb8aa3b, v67
	v_exp_f32_e32 v56, v56
	v_mul_f32_e32 v51, 0xbfb8aa3b, v64
	s_waitcnt vmcnt(13)
	v_mul_f32_e32 v60, 0xbfb8aa3b, v70
	s_waitcnt vmcnt(12)
	v_mul_f32_e32 v61, 0xbfb8aa3b, v71
	v_exp_f32_e32 v60, v60
	v_mul_f32_e32 v58, 0xbfb8aa3b, v68
	v_exp_f32_e32 v50, v50
	v_exp_f32_e32 v57, v57
	v_exp_f32_e32 v61, v61
	v_mul_f32_e32 v55, 0xbfb8aa3b, v65
	v_mul_f32_e32 v59, 0xbfb8aa3b, v69
	v_exp_f32_e32 v51, v51
	v_exp_f32_e32 v58, v58
	v_exp_f32_e32 v55, v55
	v_exp_f32_e32 v59, v59
	v_add_f32_e32 v45, 1.0, v45
	s_waitcnt vmcnt(3)
	v_mul_f32_e32 v77, 0xbfb8aa3b, v48
	s_waitcnt vmcnt(2)
	v_mul_f32_e32 v78, 0xbfb8aa3b, v42
	v_exp_f32_e32 v77, v77
	s_waitcnt vmcnt(1)
	v_mul_f32_e32 v79, 0xbfb8aa3b, v43
	v_exp_f32_e32 v78, v78
	s_waitcnt vmcnt(0)
	v_mul_f32_e32 v80, 0xbfb8aa3b, v44
	v_exp_f32_e32 v79, v79
	v_mul_f32_e32 v72, 0xbfb8aa3b, v52
	v_exp_f32_e32 v80, v80
	v_add_f32_e32 v49, 1.0, v49
	v_add_f32_e32 v56, 1.0, v56
	v_add_f32_e32 v60, 1.0, v60
	v_div_scale_f32 v81, s[4:5], v45, v45, v28
	v_mul_f32_e32 v73, 0xbfb8aa3b, v53
	v_exp_f32_e32 v72, v72
	v_add_f32_e32 v50, 1.0, v50
	v_add_f32_e32 v57, 1.0, v57
	v_add_f32_e32 v61, 1.0, v61
	v_div_scale_f32 v83, s[4:5], v49, v49, v62
	v_div_scale_f32 v91, s[4:5], v56, v56, v66
	v_add_f32_e32 v77, 1.0, v77
	v_div_scale_f32 v99, s[4:5], v60, v60, v70
	v_rcp_f32_e32 v103, v81
	v_mul_f32_e32 v74, 0xbfb8aa3b, v46
	v_exp_f32_e32 v73, v73
	v_add_f32_e32 v51, 1.0, v51
	v_add_f32_e32 v58, 1.0, v58
	v_div_scale_f32 v84, s[4:5], v50, v50, v63
	v_div_scale_f32 v93, s[4:5], v57, v57, v67
	v_add_f32_e32 v78, 1.0, v78
	v_div_scale_f32 v101, s[10:11], v61, v61, v71
	v_rcp_f32_e32 v104, v83
	v_rcp_f32_e32 v108, v91
	v_div_scale_f32 v121, s[10:11], v77, v77, v48
	v_rcp_f32_e32 v124, v99
	v_exp_f32_e32 v74, v74
	v_add_f32_e32 v55, 1.0, v55
	v_add_f32_e32 v59, 1.0, v59
	v_div_scale_f32 v87, s[4:5], v51, v51, v64
	v_div_scale_f32 v95, s[4:5], v58, v58, v68
	v_add_f32_e32 v79, 1.0, v79
	v_rcp_f32_e32 v105, v84
	v_rcp_f32_e32 v115, v93
	v_div_scale_f32 v125, s[10:11], v78, v78, v42
	v_rcp_f32_e32 v128, v101
	v_rcp_f32_e32 v137, v121
	v_div_scale_f32 v88, s[4:5], v55, v55, v65
	v_div_scale_f32 v97, s[4:5], v59, v59, v69
	v_add_f32_e32 v80, 1.0, v80
	v_rcp_f32_e32 v106, v87
	v_rcp_f32_e32 v116, v95
	v_div_scale_f32 v126, s[10:11], v79, v79, v43
	v_rcp_f32_e32 v138, v125
	v_mul_f32_e32 v75, 0xbfb8aa3b, v47
	v_add_f32_e32 v72, 1.0, v72
	v_rcp_f32_e32 v107, v88
	v_rcp_f32_e32 v123, v97
	v_div_scale_f32 v127, s[10:11], v80, v80, v44
	v_rcp_f32_e32 v139, v126
	v_fma_f32 v141, -v81, v103, 1.0
	v_mul_f32_e32 v76, 0xbfb8aa3b, v54
	v_exp_f32_e32 v75, v75
	v_div_scale_f32 v82, vcc, v28, v45, v28
	v_add_f32_e32 v73, 1.0, v73
	v_div_scale_f32 v109, s[10:11], v72, v72, v52
	v_rcp_f32_e32 v140, v127
	v_fma_f32 v142, -v83, v104, 1.0
	v_fma_f32 v146, -v91, v108, 1.0
	v_fma_f32 v150, -v99, v124, 1.0
	v_fmac_f32_e32 v103, v141, v103
	v_exp_f32_e32 v76, v76
	v_div_scale_f32 v85, s[34:35], v62, v49, v62
	v_add_f32_e32 v74, 1.0, v74
	v_div_scale_f32 v111, s[10:11], v73, v73, v53
	v_rcp_f32_e32 v132, v109
	v_fma_f32 v143, -v84, v105, 1.0
	v_fma_f32 v147, -v93, v115, 1.0
	v_fma_f32 v151, -v101, v128, 1.0
	v_fmac_f32_e32 v104, v142, v104
	v_fmac_f32_e32 v108, v146, v108
	v_fma_f32 v146, -v121, v137, 1.0
	v_fmac_f32_e32 v124, v150, v124
	v_mul_f32_e32 v150, v82, v103
	v_div_scale_f32 v86, s[30:31], v63, v50, v63
	v_div_scale_f32 v113, s[10:11], v74, v74, v46
	v_rcp_f32_e32 v133, v111
	v_fma_f32 v144, -v87, v106, 1.0
	v_fma_f32 v148, -v95, v116, 1.0
	v_fmac_f32_e32 v105, v143, v105
	v_fmac_f32_e32 v115, v147, v115
	v_fma_f32 v147, -v125, v138, 1.0
	v_fmac_f32_e32 v128, v151, v128
	v_mul_f32_e32 v151, v85, v104
	v_fmac_f32_e32 v137, v146, v137
	v_fma_f32 v146, -v81, v150, v82
	v_div_scale_f32 v89, s[28:29], v64, v51, v64
	v_rcp_f32_e32 v134, v113
	v_fma_f32 v145, -v88, v107, 1.0
	v_fma_f32 v149, -v97, v123, 1.0
	v_fmac_f32_e32 v106, v144, v106
	v_fmac_f32_e32 v116, v148, v116
	v_fma_f32 v148, -v126, v139, 1.0
	v_mul_f32_e32 v152, v86, v105
	v_fmac_f32_e32 v138, v147, v138
	v_fma_f32 v147, -v83, v151, v85
	v_fmac_f32_e32 v150, v146, v103
	v_div_scale_f32 v90, s[24:25], v65, v55, v65
	v_add_f32_e32 v75, 1.0, v75
	v_fmac_f32_e32 v107, v145, v107
	v_fmac_f32_e32 v123, v149, v123
	v_fma_f32 v149, -v127, v140, 1.0
	v_mul_f32_e32 v153, v89, v106
	v_fmac_f32_e32 v139, v148, v139
	v_fma_f32 v148, -v84, v152, v86
	v_fmac_f32_e32 v151, v147, v104
	v_fma_f32 v81, -v81, v150, v82
	v_div_scale_f32 v92, s[18:19], v66, v56, v66
	v_add_f32_e32 v76, 1.0, v76
	v_div_scale_f32 v117, s[10:11], v75, v75, v47
	v_fma_f32 v141, -v109, v132, 1.0
	v_mul_f32_e32 v154, v90, v107
	v_fmac_f32_e32 v140, v149, v140
	v_fma_f32 v149, -v87, v153, v89
	v_fmac_f32_e32 v152, v148, v105
	v_fma_f32 v82, -v83, v151, v85
	v_div_fmas_f32 v81, v81, v103, v150
	s_mov_b64 vcc, s[34:35]
	v_div_scale_f32 v110, s[40:41], v52, v72, v52
	v_div_scale_f32 v119, s[10:11], v76, v76, v54
	v_rcp_f32_e32 v135, v117
	v_fma_f32 v142, -v111, v133, 1.0
	v_mul_f32_e32 v155, v92, v108
	v_fmac_f32_e32 v132, v141, v132
	v_fma_f32 v156, -v88, v154, v90
	v_fmac_f32_e32 v153, v149, v106
	v_fma_f32 v83, -v84, v152, v86
	v_div_fmas_f32 v82, v82, v104, v151
	v_div_fixup_f32 v28, v81, v45, v28
	s_mov_b64 vcc, s[30:31]
	v_div_scale_f32 v94, s[12:13], v67, v57, v67
	v_div_scale_f32 v112, s[38:39], v53, v73, v53
	v_rcp_f32_e32 v136, v119
	v_fma_f32 v143, -v113, v134, 1.0
	v_fmac_f32_e32 v133, v142, v133
	v_fma_f32 v157, -v91, v155, v92
	v_mul_f32_e32 v158, v110, v132
	v_fmac_f32_e32 v154, v156, v107
	v_fma_f32 v84, -v87, v153, v89
	v_pk_fma_f32 v[40:41], v[28:29], v[14:15], v[40:41] op_sel_hi:[0,1,1]
	v_pk_fma_f32 v[38:39], v[28:29], v[16:17], v[38:39] op_sel_hi:[0,1,1]
	v_div_fmas_f32 v45, v83, v105, v152
	v_div_fixup_f32 v28, v82, v49, v62
	s_mov_b64 vcc, s[28:29]
	v_div_scale_f32 v114, s[36:37], v46, v74, v46
	v_fmac_f32_e32 v134, v143, v134
	v_mul_f32_e32 v141, v94, v115
	v_mul_f32_e32 v159, v112, v133
	v_fmac_f32_e32 v155, v157, v108
	v_fma_f32 v146, -v109, v158, v110
	v_fma_f32 v85, -v88, v154, v90
	v_pk_fma_f32 v[36:37], v[28:29], v[14:15], v[36:37] op_sel_hi:[0,1,1]
	v_pk_fma_f32 v[34:35], v[28:29], v[16:17], v[34:35] op_sel_hi:[0,1,1]
	v_div_fixup_f32 v28, v45, v50, v63
	v_div_fmas_f32 v45, v84, v106, v153
	s_mov_b64 vcc, s[24:25]
	v_mul_f32_e32 v160, v114, v134
	v_fma_f32 v161, -v93, v141, v94
	v_fma_f32 v147, -v111, v159, v112
	v_fma_f32 v86, -v91, v155, v92
	v_fmac_f32_e32 v158, v146, v132
	v_pk_fma_f32 v[32:33], v[28:29], v[14:15], v[32:33] op_sel_hi:[0,1,1]
	v_pk_fma_f32 v[26:27], v[28:29], v[16:17], v[26:27] op_sel_hi:[0,1,1]
	v_div_fmas_f32 v49, v85, v107, v154
	v_div_fixup_f32 v28, v45, v51, v64
	s_mov_b64 vcc, s[18:19]
	v_div_scale_f32 v96, s[8:9], v68, v58, v68
	v_fma_f32 v144, -v117, v135, 1.0
	v_fma_f32 v148, -v113, v160, v114
	v_fmac_f32_e32 v141, v161, v115
	v_fmac_f32_e32 v159, v147, v133
	v_fma_f32 v92, -v109, v158, v110
	v_pk_fma_f32 v[24:25], v[28:29], v[14:15], v[24:25] op_sel_hi:[0,1,1]
	v_pk_fma_f32 v[22:23], v[28:29], v[16:17], v[22:23] op_sel_hi:[0,1,1]
	v_div_fixup_f32 v28, v49, v55, v65
	v_div_fmas_f32 v45, v86, v108, v155
	s_mov_b64 vcc, s[40:41]
	v_div_scale_f32 v118, s[26:27], v47, v75, v47
	v_fma_f32 v145, -v119, v136, 1.0
	v_mul_f32_e32 v142, v96, v116
	v_fmac_f32_e32 v135, v144, v135
	v_fmac_f32_e32 v160, v148, v134
	v_fma_f32 v87, -v93, v141, v94
	v_fma_f32 v93, -v111, v159, v112
	v_pk_fma_f32 v[14:15], v[28:29], v[14:15], v[20:21] op_sel_hi:[0,1,1]
	v_pk_fma_f32 v[16:17], v[28:29], v[16:17], v[18:19] op_sel_hi:[0,1,1]
	v_div_fmas_f32 v28, v92, v132, v158
	v_div_fixup_f32 v18, v45, v56, v66
	s_mov_b64 vcc, s[38:39]
	v_div_scale_f32 v120, s[22:23], v54, v76, v54
	v_fmac_f32_e32 v136, v145, v136
	v_fma_f32 v162, -v95, v142, v96
	v_mul_f32_e32 v163, v118, v135
	v_fma_f32 v94, -v113, v160, v114
	v_pk_fma_f32 v[20:21], v[18:19], v[10:11], v[40:41] op_sel_hi:[0,1,1]
	v_pk_fma_f32 v[18:19], v[18:19], v[12:13], v[38:39] op_sel_hi:[0,1,1]
	v_div_fmas_f32 v38, v93, v133, v159
	v_div_fixup_f32 v28, v28, v72, v52
	s_mov_b64 vcc, s[36:37]
	v_div_scale_f32 v98, s[6:7], v69, v59, v69
	v_div_scale_f32 v122, s[20:21], v48, v77, v48
	v_mul_f32_e32 v164, v120, v136
	v_fmac_f32_e32 v142, v162, v116
	v_fma_f32 v149, -v117, v163, v118
	v_pk_fma_f32 v[36:37], v[28:29], v[10:11], v[36:37] op_sel_hi:[0,1,1]
	v_pk_fma_f32 v[34:35], v[28:29], v[12:13], v[34:35] op_sel_hi:[0,1,1]
	v_div_fmas_f32 v39, v94, v134, v160
	v_div_fixup_f32 v28, v38, v73, v53
	s_mov_b64 vcc, s[12:13]
	v_mul_f32_e32 v143, v98, v123
	v_mul_f32_e32 v165, v122, v137
	v_fma_f32 v156, -v119, v164, v120
	v_fma_f32 v88, -v95, v142, v96
	v_fmac_f32_e32 v163, v149, v135
	v_pk_fma_f32 v[32:33], v[28:29], v[10:11], v[32:33] op_sel_hi:[0,1,1]
	v_pk_fma_f32 v[26:27], v[28:29], v[12:13], v[26:27] op_sel_hi:[0,1,1]
	v_div_fmas_f32 v38, v87, v115, v141
	v_div_fixup_f32 v28, v39, v74, v46
	s_mov_b64 vcc, s[8:9]
	v_div_scale_f32 v100, s[4:5], v70, v60, v70
	v_fma_f32 v166, -v97, v143, v98
	v_fma_f32 v157, -v121, v165, v122
	v_fmac_f32_e32 v164, v156, v136
	v_fma_f32 v95, -v117, v163, v118
	v_pk_fma_f32 v[24:25], v[28:29], v[10:11], v[24:25] op_sel_hi:[0,1,1]
	v_pk_fma_f32 v[22:23], v[28:29], v[12:13], v[22:23] op_sel_hi:[0,1,1]
	v_div_fixup_f32 v28, v38, v57, v67
	v_div_fmas_f32 v38, v88, v116, v142
	s_mov_b64 vcc, s[26:27]
	v_div_scale_f32 v129, s[16:17], v42, v78, v42
	v_mul_f32_e32 v144, v100, v124
	v_fmac_f32_e32 v143, v166, v123
	v_fmac_f32_e32 v165, v157, v137
	v_fma_f32 v96, -v119, v164, v120
	v_pk_fma_f32 v[10:11], v[28:29], v[10:11], v[14:15] op_sel_hi:[0,1,1]
	v_pk_fma_f32 v[12:13], v[28:29], v[12:13], v[16:17] op_sel_hi:[0,1,1]
	v_div_fmas_f32 v28, v95, v135, v163
	v_div_fixup_f32 v14, v38, v58, v68
	s_mov_b64 vcc, s[22:23]
	v_div_scale_f32 v130, s[14:15], v43, v79, v43
	v_fma_f32 v167, -v99, v144, v100
	v_mul_f32_e32 v169, v129, v138
	v_fma_f32 v89, -v97, v143, v98
	v_fma_f32 v97, -v121, v165, v122
	v_pk_fma_f32 v[16:17], v[14:15], v[6:7], v[20:21] op_sel_hi:[0,1,1]
	v_pk_fma_f32 v[14:15], v[14:15], v[8:9], v[18:19] op_sel_hi:[0,1,1]
	v_div_fmas_f32 v38, v96, v136, v164
	v_div_fixup_f32 v18, v28, v75, v47
	s_mov_b64 vcc, s[20:21]
	v_div_scale_f32 v131, s[10:11], v44, v80, v44
	v_mul_f32_e32 v170, v130, v139
	v_fmac_f32_e32 v144, v167, v124
	v_fma_f32 v161, -v125, v169, v129
	v_pk_fma_f32 v[20:21], v[18:19], v[6:7], v[36:37] op_sel_hi:[0,1,1]
	v_pk_fma_f32 v[18:19], v[18:19], v[8:9], v[34:35] op_sel_hi:[0,1,1]
	v_div_fmas_f32 v34, v97, v137, v165
	v_div_fixup_f32 v28, v38, v76, v54
	s_mov_b64 vcc, s[6:7]
	v_div_scale_f32 v102, s[42:43], v71, v61, v71
	v_mul_f32_e32 v171, v131, v140
	v_fma_f32 v162, -v126, v170, v130
	v_fma_f32 v90, -v99, v144, v100
	v_fmac_f32_e32 v169, v161, v138
	v_pk_fma_f32 v[32:33], v[28:29], v[6:7], v[32:33] op_sel_hi:[0,1,1]
	v_pk_fma_f32 v[26:27], v[28:29], v[8:9], v[26:27] op_sel_hi:[0,1,1]
	v_div_fmas_f32 v35, v89, v123, v143
	v_div_fixup_f32 v28, v34, v77, v48
	s_mov_b64 vcc, s[4:5]
	v_mul_f32_e32 v145, v102, v128
	v_fma_f32 v166, -v127, v171, v131
	v_fmac_f32_e32 v170, v162, v139
	v_fma_f32 v98, -v125, v169, v129
	v_pk_fma_f32 v[24:25], v[28:29], v[6:7], v[24:25] op_sel_hi:[0,1,1]
	v_pk_fma_f32 v[22:23], v[28:29], v[8:9], v[22:23] op_sel_hi:[0,1,1]
	v_div_fixup_f32 v28, v35, v59, v69
	v_div_fmas_f32 v34, v90, v124, v144
	s_mov_b64 vcc, s[16:17]
	v_fma_f32 v168, -v101, v145, v102
	v_fmac_f32_e32 v171, v166, v140
	v_fma_f32 v99, -v126, v170, v130
	v_pk_fma_f32 v[6:7], v[28:29], v[6:7], v[10:11] op_sel_hi:[0,1,1]
	v_div_fixup_f32 v10, v34, v60, v70
	v_div_fmas_f32 v11, v98, v138, v169
	s_mov_b64 vcc, s[14:15]
	v_fmac_f32_e32 v145, v168, v128
	v_fma_f32 v100, -v127, v171, v131
	v_pk_fma_f32 v[40:41], v[10:11], v[2:3], v[16:17] op_sel_hi:[0,1,1]
	v_pk_fma_f32 v[38:39], v[10:11], v[4:5], v[14:15] op_sel_hi:[0,1,1]
	v_div_fixup_f32 v10, v11, v78, v42
	v_div_fmas_f32 v11, v99, v139, v170
	s_mov_b64 vcc, s[10:11]
	v_fma_f32 v91, -v101, v145, v102
	v_pk_fma_f32 v[36:37], v[10:11], v[2:3], v[20:21] op_sel_hi:[0,1,1]
	v_pk_fma_f32 v[34:35], v[10:11], v[4:5], v[18:19] op_sel_hi:[0,1,1]
	v_div_fixup_f32 v10, v11, v79, v43
	v_div_fmas_f32 v11, v100, v140, v171
	s_mov_b64 vcc, s[42:43]
	v_pk_fma_f32 v[32:33], v[10:11], v[2:3], v[32:33] op_sel_hi:[0,1,1]
	v_pk_fma_f32 v[26:27], v[10:11], v[4:5], v[26:27] op_sel_hi:[0,1,1]
	v_div_fixup_f32 v10, v11, v80, v44
	v_div_fmas_f32 v11, v91, v128, v145
	v_pk_fma_f32 v[8:9], v[28:29], v[8:9], v[12:13] op_sel_hi:[0,1,1]
	v_pk_fma_f32 v[24:25], v[10:11], v[2:3], v[24:25] op_sel_hi:[0,1,1]
	v_pk_fma_f32 v[22:23], v[10:11], v[4:5], v[22:23] op_sel_hi:[0,1,1]
	v_div_fixup_f32 v10, v11, v61, v71
	v_pk_fma_f32 v[20:21], v[10:11], v[2:3], v[6:7] op_sel_hi:[0,1,1]
	v_pk_fma_f32 v[18:19], v[10:11], v[4:5], v[8:9] op_sel_hi:[0,1,1]
	s_cbranch_scc0 .LBB0_17
	v_mbcnt_lo_u32_b32 v1, -1, 0
	v_mbcnt_hi_u32_b32 v1, -1, v1
	v_and_b32_e32 v3, 64, v1
	v_xor_b32_e32 v2, 8, v1
	v_add_u32_e32 v4, 64, v3
	v_cmp_lt_i32_e32 vcc, v2, v4
	v_xor_b32_e32 v5, 32, v1
	s_nop 0
	v_cndmask_b32_e32 v2, v1, v2, vcc
	v_lshlrev_b32_e32 v42, 2, v2
	v_xor_b32_e32 v2, 16, v1
	v_cmp_lt_i32_e32 vcc, v2, v4
	ds_bpermute_b32 v3, v42, v41
	ds_bpermute_b32 v14, v42, v34
	v_cndmask_b32_e32 v2, v1, v2, vcc
	v_cmp_lt_i32_e32 vcc, v5, v4
	v_lshlrev_b32_e32 v43, 2, v2
	ds_bpermute_b32 v2, v42, v40
	v_cndmask_b32_e32 v1, v1, v5, vcc
	ds_bpermute_b32 v4, v42, v38
	ds_bpermute_b32 v5, v42, v39
	ds_bpermute_b32 v15, v42, v35
	ds_bpermute_b32 v16, v42, v32
	ds_bpermute_b32 v17, v42, v33
	s_waitcnt lgkmcnt(5)
	v_pk_add_f32 v[2:3], v[40:41], v[2:3]
	s_waitcnt lgkmcnt(3)
	v_pk_add_f32 v[8:9], v[38:39], v[4:5]
	s_waitcnt lgkmcnt(2)
	v_pk_add_f32 v[14:15], v[34:35], v[14:15]
	ds_bpermute_b32 v34, v42, v24
	s_waitcnt lgkmcnt(1)
	v_pk_add_f32 v[30:31], v[32:33], v[16:17]
	ds_bpermute_b32 v35, v42, v25
	ds_bpermute_b32 v6, v43, v2
	ds_bpermute_b32 v7, v43, v3
	ds_bpermute_b32 v10, v43, v8
	ds_bpermute_b32 v11, v43, v9
	ds_bpermute_b32 v12, v42, v36
	ds_bpermute_b32 v13, v42, v37
	ds_bpermute_b32 v28, v43, v14
	ds_bpermute_b32 v29, v43, v15
	ds_bpermute_b32 v32, v43, v30
	ds_bpermute_b32 v33, v43, v31
	s_waitcnt lgkmcnt(10)
	v_pk_add_f32 v[24:25], v[24:25], v[34:35]
	s_waitcnt lgkmcnt(8)
	v_pk_add_f32 v[2:3], v[2:3], v[6:7]
	s_waitcnt lgkmcnt(6)
	v_pk_add_f32 v[6:7], v[8:9], v[10:11]
	s_waitcnt lgkmcnt(4)
	v_pk_add_f32 v[10:11], v[36:37], v[12:13]
	s_waitcnt lgkmcnt(2)
	v_pk_add_f32 v[16:17], v[14:15], v[28:29]
	s_waitcnt lgkmcnt(0)
	v_pk_add_f32 v[14:15], v[30:31], v[32:33]
	ds_bpermute_b32 v32, v42, v26
	ds_bpermute_b32 v33, v42, v27
	ds_bpermute_b32 v34, v43, v24
	ds_bpermute_b32 v35, v43, v25
	ds_bpermute_b32 v36, v42, v22
	ds_bpermute_b32 v37, v42, v23
	ds_bpermute_b32 v38, v42, v20
	ds_bpermute_b32 v39, v42, v21
	ds_bpermute_b32 v40, v42, v18
	ds_bpermute_b32 v41, v42, v19
	s_waitcnt lgkmcnt(8)
	v_pk_add_f32 v[26:27], v[26:27], v[32:33]
	s_waitcnt lgkmcnt(6)
	v_pk_add_f32 v[24:25], v[24:25], v[34:35]
	s_waitcnt lgkmcnt(4)
	v_pk_add_f32 v[34:35], v[22:23], v[36:37]
	s_waitcnt lgkmcnt(2)
	v_pk_add_f32 v[20:21], v[20:21], v[38:39]
	s_waitcnt lgkmcnt(0)
	v_pk_add_f32 v[40:41], v[18:19], v[40:41]
	ds_bpermute_b32 v12, v43, v10
	ds_bpermute_b32 v13, v43, v11
	ds_bpermute_b32 v32, v43, v26
	ds_bpermute_b32 v33, v43, v27
	ds_bpermute_b32 v36, v43, v34
	ds_bpermute_b32 v37, v43, v35
	ds_bpermute_b32 v38, v43, v20
	ds_bpermute_b32 v39, v43, v21
	ds_bpermute_b32 v42, v43, v40
	ds_bpermute_b32 v43, v43, v41
	v_lshlrev_b32_e32 v1, 2, v1
	s_waitcnt lgkmcnt(8)
	v_pk_add_f32 v[10:11], v[10:11], v[12:13]
	s_waitcnt lgkmcnt(6)
	v_pk_add_f32 v[26:27], v[26:27], v[32:33]
	s_waitcnt lgkmcnt(4)
	v_pk_add_f32 v[34:35], v[34:35], v[36:37]
	s_waitcnt lgkmcnt(2)
	v_pk_add_f32 v[18:19], v[20:21], v[38:39]
	s_waitcnt lgkmcnt(0)
	v_pk_add_f32 v[38:39], v[40:41], v[42:43]
	ds_bpermute_b32 v4, v1, v2
	ds_bpermute_b32 v5, v1, v3
	ds_bpermute_b32 v8, v1, v6
	ds_bpermute_b32 v9, v1, v7
	ds_bpermute_b32 v12, v1, v10
	ds_bpermute_b32 v13, v1, v11
	ds_bpermute_b32 v28, v1, v16
	ds_bpermute_b32 v29, v1, v17
	ds_bpermute_b32 v30, v1, v14
	ds_bpermute_b32 v31, v1, v15
	ds_bpermute_b32 v32, v1, v26
	ds_bpermute_b32 v33, v1, v27
	ds_bpermute_b32 v22, v1, v24
	ds_bpermute_b32 v23, v1, v25
	ds_bpermute_b32 v36, v1, v34
	ds_bpermute_b32 v37, v1, v35
	ds_bpermute_b32 v20, v1, v18
	ds_bpermute_b32 v21, v1, v19
	ds_bpermute_b32 v40, v1, v38
	ds_bpermute_b32 v41, v1, v39
	v_cmp_gt_u32_e32 vcc, 8, v218
	s_and_saveexec_b64 s[4:5], vcc
	s_cbranch_execz .LBB0_20
	s_mul_i32 s2, s78, 0x280
	s_add_i32 s2, s2, 0
	v_lshl_add_u32 v1, v218, 4, s2
	s_waitcnt lgkmcnt(14)
	v_pk_add_f32 v[2:3], v[2:3], v[4:5]
	v_pk_add_f32 v[4:5], v[6:7], v[8:9]
	ds_write_b128 v1, v[2:5]
	v_pk_add_f32 v[2:3], v[10:11], v[12:13]
	s_waitcnt lgkmcnt(13)
	v_pk_add_f32 v[4:5], v[16:17], v[28:29]
	ds_write_b128 v1, v[2:5] offset:128
	s_waitcnt lgkmcnt(12)
	v_pk_add_f32 v[2:3], v[14:15], v[30:31]
	s_waitcnt lgkmcnt(10)
	v_pk_add_f32 v[4:5], v[26:27], v[32:33]
	ds_write_b128 v1, v[2:5] offset:256
	s_waitcnt lgkmcnt(9)
	v_pk_add_f32 v[2:3], v[24:25], v[22:23]
	s_waitcnt lgkmcnt(7)
	v_pk_add_f32 v[4:5], v[34:35], v[36:37]
	ds_write_b128 v1, v[2:5] offset:384
	s_waitcnt lgkmcnt(6)
	v_pk_add_f32 v[2:3], v[18:19], v[20:21]
	s_waitcnt lgkmcnt(4)
	v_pk_add_f32 v[4:5], v[38:39], v[40:41]
	ds_write_b128 v1, v[2:5] offset:512

.LBB0_109:
	s_lshl_b32 s11, s6, 1
	s_lshl_b32 s14, s7, 1
	v_or_b32_e32 v4, s11, v1
	v_or_b32_e32 v60, s14, v2
	s_add_i32 s15, s11, 4
	s_add_i32 s35, s14, 4
	s_add_i32 s36, s11, 8
	s_add_i32 s37, s14, 8
	s_add_i32 s38, s11, 12
	s_add_i32 s39, s14, 12
	s_add_i32 s40, s11, 16
	s_add_i32 s41, s14, 16
	s_add_i32 s42, s11, 20
	s_add_i32 s43, s14, 20
	s_add_i32 s44, s11, 24
	s_add_i32 s45, s14, 24
	s_add_i32 s11, s11, 28
	s_add_i32 s14, s14, 28
	v_add_u32_e32 v28, s4, v60
	v_or_b32_e32 v61, s15, v1
	v_or_b32_e32 v62, s35, v2
	v_or_b32_e32 v63, s36, v1
	v_or_b32_e32 v64, s37, v2
	v_or_b32_e32 v65, s38, v1
	v_or_b32_e32 v66, s39, v2
	v_or_b32_e32 v67, s40, v1
	v_or_b32_e32 v68, s41, v2
	v_or_b32_e32 v69, s42, v1
	v_or_b32_e32 v70, s43, v2
	v_or_b32_e32 v71, s44, v1
	v_or_b32_e32 v72, s45, v2
	v_or_b32_e32 v73, s11, v1
	v_or_b32_e32 v74, s14, v2
	v_add_u32_e32 v30, s5, v4
	v_mad_i64_i32 v[28:29], s[14:15], v28, s34, v[14:15]
	v_add_u32_e32 v34, s5, v61
	v_add_u32_e32 v32, s4, v62
	v_add_u32_e32 v38, s5, v63
	v_add_u32_e32 v36, s4, v64
	v_add_u32_e32 v42, s5, v65
	v_add_u32_e32 v40, s4, v66
	v_add_u32_e32 v46, s5, v67
	v_add_u32_e32 v44, s4, v68
	v_add_u32_e32 v50, s5, v69
	v_add_u32_e32 v48, s4, v70
	v_add_u32_e32 v54, s5, v71
	v_add_u32_e32 v52, s4, v72
	v_add_u32_e32 v58, s5, v73
	v_add_u32_e32 v56, s4, v74
	v_mad_i64_i32 v[30:31], s[14:15], v30, s34, v[14:15]
	v_mad_i64_i32 v[32:33], s[14:15], v32, s34, v[14:15]
	v_mad_i64_i32 v[34:35], s[14:15], v34, s34, v[14:15]
	v_mad_i64_i32 v[36:37], s[14:15], v36, s34, v[14:15]
	v_mad_i64_i32 v[38:39], s[14:15], v38, s34, v[14:15]
	v_mad_i64_i32 v[40:41], s[14:15], v40, s34, v[14:15]
	v_mad_i64_i32 v[42:43], s[14:15], v42, s34, v[14:15]
	v_mad_i64_i32 v[44:45], s[14:15], v44, s34, v[14:15]
	v_mad_i64_i32 v[46:47], s[14:15], v46, s34, v[14:15]
	v_mad_i64_i32 v[48:49], s[14:15], v48, s34, v[14:15]
	v_mad_i64_i32 v[50:51], s[14:15], v50, s34, v[14:15]
	v_mad_i64_i32 v[52:53], s[14:15], v52, s34, v[14:15]
	v_mad_i64_i32 v[54:55], s[14:15], v54, s34, v[14:15]
	v_mad_i64_i32 v[56:57], s[14:15], v56, s34, v[14:15]
	v_mad_i64_i32 v[58:59], s[14:15], v58, s34, v[14:15]
	global_load_dword v75, v[28:29], off nt
	global_load_dword v76, v[30:31], off nt
	global_load_dword v77, v[32:33], off nt
	global_load_dword v78, v[34:35], off nt
	global_load_dword v79, v[36:37], off nt
	global_load_dword v80, v[38:39], off nt
	global_load_dword v81, v[40:41], off nt
	global_load_dword v82, v[42:43], off nt
	global_load_dword v83, v[44:45], off nt
	global_load_dword v84, v[46:47], off nt
	global_load_dword v85, v[48:49], off nt
	global_load_dword v86, v[50:51], off nt
	global_load_dword v87, v[52:53], off nt
	global_load_dword v88, v[54:55], off nt
	global_load_dword v89, v[56:57], off nt
	global_load_dword v90, v[58:59], off nt
	s_add_i32 s7, s7, 16
	s_add_i32 s6, s6, 16
	s_add_i32 s10, s10, -16
	v_mad_u64_u32 v[28:29], s[14:15], v60, s2, v[8:9]
	s_cmp_lg_u32 s10, 0
	v_mad_u64_u32 v[30:31], s[14:15], v4, s2, v[8:9]
	v_mad_u64_u32 v[32:33], s[14:15], v62, s2, v[8:9]
	v_mad_u64_u32 v[34:35], s[14:15], v61, s2, v[8:9]
	v_mad_u64_u32 v[36:37], s[14:15], v64, s2, v[8:9]
	v_mad_u64_u32 v[38:39], s[14:15], v63, s2, v[8:9]
	v_mad_u64_u32 v[40:41], s[14:15], v66, s2, v[8:9]
	v_mad_u64_u32 v[42:43], s[14:15], v65, s2, v[8:9]
	v_mad_u64_u32 v[44:45], s[14:15], v68, s2, v[8:9]
	v_mad_u64_u32 v[46:47], s[14:15], v67, s2, v[8:9]
	v_mad_u64_u32 v[48:49], s[14:15], v70, s2, v[8:9]
	v_mad_u64_u32 v[50:51], s[14:15], v69, s2, v[8:9]
	v_mad_u64_u32 v[52:53], s[14:15], v72, s2, v[8:9]
	v_mad_u64_u32 v[54:55], s[14:15], v71, s2, v[8:9]
	v_mad_u64_u32 v[56:57], s[14:15], v74, s2, v[8:9]
	v_mad_u64_u32 v[58:59], s[14:15], v73, s2, v[8:9]
	s_waitcnt vmcnt(15)
	ds_write_b32 v28, v75
	s_waitcnt vmcnt(14)
	ds_write_b32 v30, v76
	s_waitcnt vmcnt(13)
	ds_write_b32 v32, v77
	s_waitcnt vmcnt(12)
	ds_write_b32 v34, v78
	s_waitcnt vmcnt(11)
	ds_write_b32 v36, v79
	s_waitcnt vmcnt(10)
	ds_write_b32 v38, v80
	s_waitcnt vmcnt(9)
	ds_write_b32 v40, v81
	s_waitcnt vmcnt(8)
	ds_write_b32 v42, v82
	s_waitcnt vmcnt(7)
	ds_write_b32 v44, v83
	s_waitcnt vmcnt(6)
	ds_write_b32 v46, v84
	s_waitcnt vmcnt(5)
	ds_write_b32 v48, v85
	s_waitcnt vmcnt(4)
	ds_write_b32 v50, v86
	s_waitcnt vmcnt(3)
	ds_write_b32 v52, v87
	s_waitcnt vmcnt(2)
	ds_write_b32 v54, v88
	s_waitcnt vmcnt(1)
	ds_write_b32 v56, v89
	s_waitcnt vmcnt(0)
	ds_write_b32 v58, v90
	s_cbranch_scc1 .LBB0_109
	s_waitcnt lgkmcnt(0)
	ds_read2_b32 v[34:35], v19 offset0:33 offset1:41
	ds_read2_b32 v[36:37], v19 offset0:66 offset1:74
	ds_read2_b32 v[38:39], v19 offset0:231 offset1:239
	ds_read2_b32 v[40:41], v19 offset0:165 offset1:173
	ds_read2_b32 v[42:43], v19 offset0:99 offset1:107
	ds_read2_b32 v[44:45], v19 offset0:132 offset1:140
	ds_read2_b32 v[46:47], v19 offset0:198 offset1:206
	ds_read2_b32 v[48:49], v19 offset1:8
	s_waitcnt lgkmcnt(7)
	v_bfe_u32 v30, v34, 16, 1
	v_add3_u32 v50, v34, v30, s30
	s_waitcnt lgkmcnt(2)
	v_bfe_u32 v51, v44, 16, 1
	v_bfe_u32 v28, v40, 16, 1
	s_waitcnt lgkmcnt(0)
	v_bfe_u32 v30, v48, 16, 1
	v_bfe_u32 v31, v36, 16, 1
	v_bfe_u32 v52, v46, 16, 1
	v_add3_u32 v51, v44, v51, s30
	v_add3_u32 v30, v48, v30, s30
	v_add3_u32 v28, v40, v28, s30
	v_add3_u32 v52, v46, v52, s30
	v_add3_u32 v31, v36, v31, s30
	v_lshrrev_b32_e32 v53, 16, v30
	v_lshrrev_b32_e32 v30, 16, v51
	v_lshrrev_b32_e32 v54, 16, v31
	v_lshrrev_b32_e32 v31, 16, v52
	v_and_or_b32 v30, v28, s31, v30
	v_and_or_b32 v28, v50, s31, v53
	v_mov_b32_e32 v52, v5
	v_mov_b32_e32 v53, v5
	s_and_b32 s5, s9, 0x60
	v_cvt_pk_fp8_f32 v52, v48, v34
	v_cvt_pk_fp8_f32 v53, v44, v40
	s_or_b32 s6, s8, s5
	v_bfe_u32 v29, v42, 16, 1
	v_add_u32_e32 v50, s6, v18
	s_ashr_i32 s5, s4, 31
	v_bfe_u32 v4, v38, 16, 1
	v_add3_u32 v29, v42, v29, s30
	v_ashrrev_i32_e32 v51, 31, v50
	v_lshl_add_u64 v[14:15], s[4:5], 1, v[10:11]
	v_add3_u32 v4, v38, v4, s30
	v_and_or_b32 v29, v29, s31, v54
	v_lshlrev_b64 v[54:55], 10, v[50:51]
	v_lshlrev_b64 v[50:51], 11, v[50:51]
	v_cvt_pk_fp8_f32 v52, v36, v42 op_sel:[0,0,1]
	v_cvt_pk_fp8_f32 v53, v46, v38 op_sel:[0,0,1]
	v_and_or_b32 v31, v4, s31, v31
	v_lshl_add_u64 v[50:51], v[14:15], 0, v[50:51]
	v_lshl_add_u64 v[32:33], v[12:13], 0, s[4:5]
	global_store_dwordx4 v[50:51], v[28:31], off
	v_bfe_u32 v36, v45, 16, 1
	v_add3_u32 v36, v45, v36, s30
	v_bfe_u32 v30, v35, 16, 1
	v_lshl_add_u64 v[28:29], v[32:33], 0, v[54:55]
	v_add3_u32 v34, v35, v30, s30
	v_bfe_u32 v30, v49, 16, 1
	global_store_dwordx2 v[28:29], v[52:53], off
	v_bfe_u32 v28, v41, 16, 1
	v_add3_u32 v30, v49, v30, s30
	v_add3_u32 v28, v41, v28, s30
	v_lshrrev_b32_e32 v40, 16, v30
	v_lshrrev_b32_e32 v30, 16, v36
	v_and_or_b32 v30, v28, s31, v30
	v_and_or_b32 v28, v34, s31, v40
	v_mov_b32_e32 v34, v5
	v_cvt_pk_fp8_f32 v34, v49, v35
	v_mov_b32_e32 v35, v5
	v_cvt_pk_fp8_f32 v35, v45, v41
	v_bfe_u32 v31, v37, 16, 1
	v_bfe_u32 v38, v47, 16, 1
	v_add_u32_e32 v50, s6, v20
	v_bfe_u32 v4, v39, 16, 1
	v_bfe_u32 v29, v43, 16, 1
	v_add3_u32 v38, v47, v38, s30
	v_add3_u32 v31, v37, v31, s30
	v_ashrrev_i32_e32 v51, 31, v50
	v_cvt_pk_fp8_f32 v34, v37, v43 op_sel:[0,0,1]
	v_cvt_pk_fp8_f32 v35, v47, v39 op_sel:[0,0,1]
	v_add3_u32 v29, v43, v29, s30
	v_add3_u32 v4, v39, v4, s30
	v_lshrrev_b32_e32 v42, 16, v31
	v_lshrrev_b32_e32 v31, 16, v38
	v_lshlrev_b64 v[44:45], 11, v[50:51]
	v_and_or_b32 v31, v4, s31, v31
	v_and_or_b32 v29, v29, s31, v42
	v_lshlrev_b64 v[40:41], 10, v[50:51]
	v_lshl_add_u64 v[36:37], v[14:15], 0, v[44:45]
	global_store_dwordx4 v[36:37], v[28:31], off
	v_readlane_b32 s44, v253, 29
	v_readlane_b32 s45, v253, 30
	v_lshl_add_u64 v[28:29], v[32:33], 0, v[40:41]
	global_store_dwordx2 v[28:29], v[34:35], off
	ds_read2_b32 v[34:35], v19 offset0:16 offset1:24
	ds_read2_b32 v[36:37], v19 offset0:49 offset1:57
	ds_read2_b32 v[38:39], v19 offset0:82 offset1:90
	ds_read2_b32 v[40:41], v19 offset0:247 offset1:255
	ds_read2_b32 v[42:43], v19 offset0:181 offset1:189
	ds_read2_b32 v[44:45], v19 offset0:115 offset1:123
	ds_read2_b32 v[46:47], v19 offset0:148 offset1:156
	ds_read2_b32 v[48:49], v19 offset0:214 offset1:222
	s_waitcnt lgkmcnt(6)
	v_bfe_u32 v30, v36, 16, 1
	v_add3_u32 v50, v36, v30, s30
	v_bfe_u32 v30, v34, 16, 1
	s_waitcnt lgkmcnt(1)
	v_bfe_u32 v51, v46, 16, 1
	v_bfe_u32 v28, v42, 16, 1
	v_bfe_u32 v31, v38, 16, 1
	s_waitcnt lgkmcnt(0)
	v_bfe_u32 v52, v48, 16, 1
	v_add3_u32 v51, v46, v51, s30
	v_add3_u32 v30, v34, v30, s30
	v_add3_u32 v28, v42, v28, s30
	v_add3_u32 v52, v48, v52, s30
	v_add3_u32 v31, v38, v31, s30
	v_lshrrev_b32_e32 v53, 16, v30
	v_lshrrev_b32_e32 v30, 16, v51
	v_lshrrev_b32_e32 v54, 16, v31
	v_lshrrev_b32_e32 v31, 16, v52
	v_and_or_b32 v30, v28, s31, v30
	v_and_or_b32 v28, v50, s31, v53
	v_mov_b32_e32 v52, v5
	v_mov_b32_e32 v53, v5
	v_cvt_pk_fp8_f32 v52, v34, v36
	v_cvt_pk_fp8_f32 v53, v46, v42
	v_bfe_u32 v29, v44, 16, 1
	v_add_u32_e32 v50, s6, v21
	v_bfe_u32 v4, v40, 16, 1
	v_add3_u32 v29, v44, v29, s30
	v_ashrrev_i32_e32 v51, 31, v50
	v_add3_u32 v4, v40, v4, s30
	v_and_or_b32 v29, v29, s31, v54
	v_lshlrev_b64 v[54:55], 10, v[50:51]
	v_lshlrev_b64 v[50:51], 11, v[50:51]
	v_cvt_pk_fp8_f32 v52, v38, v44 op_sel:[0,0,1]
	v_cvt_pk_fp8_f32 v53, v48, v40 op_sel:[0,0,1]
	v_and_or_b32 v31, v4, s31, v31
	v_lshl_add_u64 v[50:51], v[14:15], 0, v[50:51]
	global_store_dwordx4 v[50:51], v[28:31], off
	v_bfe_u32 v36, v47, 16, 1
	v_add3_u32 v36, v47, v36, s30
	v_bfe_u32 v30, v37, 16, 1
	v_lshl_add_u64 v[28:29], v[32:33], 0, v[54:55]
	v_add3_u32 v34, v37, v30, s30
	v_bfe_u32 v30, v35, 16, 1
	global_store_dwordx2 v[28:29], v[52:53], off
	v_bfe_u32 v28, v43, 16, 1
	v_add3_u32 v30, v35, v30, s30
	v_add3_u32 v28, v43, v28, s30
	v_lshrrev_b32_e32 v40, 16, v30
	v_lshrrev_b32_e32 v30, 16, v36
	v_and_or_b32 v30, v28, s31, v30
	v_and_or_b32 v28, v34, s31, v40
	v_mov_b32_e32 v34, v5
	v_cvt_pk_fp8_f32 v34, v35, v37
	v_mov_b32_e32 v35, v5
	v_cvt_pk_fp8_f32 v35, v47, v43
	v_bfe_u32 v31, v39, 16, 1
	v_bfe_u32 v29, v45, 16, 1
	v_bfe_u32 v38, v49, 16, 1
	v_add3_u32 v31, v39, v31, s30
	v_add_u32_e32 v50, s6, v22
	v_bfe_u32 v4, v41, 16, 1
	v_add3_u32 v29, v45, v29, s30
	v_add3_u32 v38, v49, v38, s30
	v_lshrrev_b32_e32 v42, 16, v31
	v_ashrrev_i32_e32 v51, 31, v50
	v_cvt_pk_fp8_f32 v34, v39, v45 op_sel:[0,0,1]
	v_cvt_pk_fp8_f32 v35, v49, v41 op_sel:[0,0,1]
	v_add3_u32 v4, v41, v4, s30
	v_lshrrev_b32_e32 v31, 16, v38
	v_and_or_b32 v29, v29, s31, v42
	v_lshlrev_b64 v[42:43], 11, v[50:51]
	v_and_or_b32 v31, v4, s31, v31
	v_lshlrev_b64 v[36:37], 10, v[50:51]
	v_lshl_add_u64 v[14:15], v[14:15], 0, v[42:43]
	global_store_dwordx4 v[14:15], v[28:31], off
	v_lshl_add_u64 v[14:15], v[32:33], 0, v[36:37]
	global_store_dwordx2 v[14:15], v[34:35], off
	s_waitcnt lgkmcnt(0)
	s_branch .LBB0_82

.LBB0_245:
	v_lshl_add_u64 v[32:33], v[26:27], 1, s[16:17]
	v_readlane_b32 s16, v253, 50
	v_readlane_b32 s17, v253, 51
	s_and_b64 s[16:17], s[16:17], s[14:15]
	s_and_b64 vcc, exec, s[16:17]
	s_cbranch_vccnz .LBB0_247
	v_lshl_add_u64 v[146:147], s[94:95], 0, v[30:31]
	v_mul_lo_u32 v29, v147, s22
	v_mul_lo_u32 v31, v146, s23
	v_mad_u64_u32 v[146:147], s[14:15], v146, s22, 0
	v_add3_u32 v147, v147, v31, v29
	s_and_b64 s[14:15], s[30:31], exec
	v_lshl_add_u64 v[146:147], v[146:147], 1, v[32:33]
	s_cselect_b32 s48, 0x4000000, 64
	v_cvt_pk_bf16_f32 v18, v18, v19
	v_cvt_pk_bf16_f32 v19, v20, v21
	v_cvt_pk_bf16_f32 v20, v22, v23
	v_cvt_pk_bf16_f32 v21, v24, v25
	v_lshl_add_u64 v[22:23], v[146:147], 0, s[48:49]
	global_store_dwordx4 v[146:147], v[18:21], off nt
	s_nop 1
	v_cvt_pk_bf16_f32 v18, v164, v165
	v_cvt_pk_bf16_f32 v19, v166, v167
	v_cvt_pk_bf16_f32 v20, v168, v169
	v_cvt_pk_bf16_f32 v21, v170, v171
	global_store_dwordx4 v[22:23], v[18:21], off nt

.LBB0_266:
	v_lshl_add_u64 v[130:131], s[94:95], 0, v[130:131]
	v_mul_lo_u32 v29, v131, s22
	v_mul_lo_u32 v31, v130, s23
	v_mad_u64_u32 v[130:131], s[28:29], v130, s22, 0
	v_add3_u32 v131, v131, v31, v29
	s_and_b64 s[28:29], s[30:31], exec
	v_lshl_add_u64 v[130:131], v[130:131], 1, v[32:33]
	s_cselect_b32 s48, 0x4000000, 64
	v_cvt_pk_bf16_f32 v18, v18, v19
	v_cvt_pk_bf16_f32 v19, v20, v21
	v_cvt_pk_bf16_f32 v20, v22, v23
	v_cvt_pk_bf16_f32 v21, v24, v25
	v_lshl_add_u64 v[22:23], v[130:131], 0, s[48:49]
	global_store_dwordx4 v[130:131], v[18:21], off nt
	s_nop 1
	v_cvt_pk_bf16_f32 v18, v146, v147
	v_cvt_pk_bf16_f32 v19, v148, v149
	v_cvt_pk_bf16_f32 v20, v150, v151
	v_cvt_pk_bf16_f32 v21, v152, v153
	global_store_dwordx4 v[22:23], v[18:21], off nt

.LBB0_292:
	v_lshl_add_u64 v[114:115], s[94:95], 0, v[114:115]
	v_mul_lo_u32 v29, v115, s22
	v_mul_lo_u32 v31, v114, s23
	v_mad_u64_u32 v[114:115], s[28:29], v114, s22, 0
	v_add3_u32 v115, v115, v31, v29
	s_and_b64 s[28:29], s[30:31], exec
	v_lshl_add_u64 v[114:115], v[114:115], 1, v[32:33]
	s_cselect_b32 s48, 0x4000000, 64
	v_cvt_pk_bf16_f32 v18, v18, v19
	v_cvt_pk_bf16_f32 v19, v20, v21
	v_cvt_pk_bf16_f32 v20, v22, v23
	v_cvt_pk_bf16_f32 v21, v24, v25
	v_lshl_add_u64 v[22:23], v[114:115], 0, s[48:49]
	global_store_dwordx4 v[114:115], v[18:21], off nt
	s_nop 1
	v_cvt_pk_bf16_f32 v18, v130, v131
	v_cvt_pk_bf16_f32 v19, v132, v133
	v_cvt_pk_bf16_f32 v20, v134, v135
	v_cvt_pk_bf16_f32 v21, v136, v137
	global_store_dwordx4 v[22:23], v[18:21], off nt

.LBB0_318:
	v_lshl_add_u64 v[98:99], s[94:95], 0, v[98:99]
	v_mul_lo_u32 v29, v99, s22
	v_mul_lo_u32 v31, v98, s23
	v_mad_u64_u32 v[98:99], s[28:29], v98, s22, 0
	v_add3_u32 v99, v99, v31, v29
	s_and_b64 s[28:29], s[30:31], exec
	v_lshl_add_u64 v[98:99], v[98:99], 1, v[32:33]
	s_cselect_b32 s48, 0x4000000, 64
	v_cvt_pk_bf16_f32 v18, v18, v19
	v_cvt_pk_bf16_f32 v19, v20, v21
	v_cvt_pk_bf16_f32 v20, v22, v23
	v_cvt_pk_bf16_f32 v21, v24, v25
	v_lshl_add_u64 v[22:23], v[98:99], 0, s[48:49]
	global_store_dwordx4 v[98:99], v[18:21], off nt
	s_nop 1
	v_cvt_pk_bf16_f32 v18, v114, v115
	v_cvt_pk_bf16_f32 v19, v116, v117
	v_cvt_pk_bf16_f32 v20, v118, v119
	v_cvt_pk_bf16_f32 v21, v120, v121
	global_store_dwordx4 v[22:23], v[18:21], off nt

.LBB0_344:
	v_lshl_add_u64 v[82:83], s[94:95], 0, v[82:83]
	v_mul_lo_u32 v29, v83, s22
	v_mul_lo_u32 v31, v82, s23
	v_mad_u64_u32 v[82:83], s[28:29], v82, s22, 0
	v_add3_u32 v83, v83, v31, v29
	s_and_b64 s[28:29], s[30:31], exec
	v_lshl_add_u64 v[82:83], v[82:83], 1, v[32:33]
	s_cselect_b32 s48, 0x4000000, 64
	v_cvt_pk_bf16_f32 v18, v18, v19
	v_cvt_pk_bf16_f32 v19, v20, v21
	v_cvt_pk_bf16_f32 v20, v22, v23
	v_cvt_pk_bf16_f32 v21, v24, v25
	v_lshl_add_u64 v[22:23], v[82:83], 0, s[48:49]
	global_store_dwordx4 v[82:83], v[18:21], off nt
	s_nop 1
	v_cvt_pk_bf16_f32 v18, v98, v99
	v_cvt_pk_bf16_f32 v19, v100, v101
	v_cvt_pk_bf16_f32 v20, v102, v103
	v_cvt_pk_bf16_f32 v21, v104, v105
	global_store_dwordx4 v[22:23], v[18:21], off nt

.LBB0_370:
	v_lshl_add_u64 v[66:67], s[94:95], 0, v[66:67]
	v_mul_lo_u32 v29, v67, s22
	v_mul_lo_u32 v31, v66, s23
	v_mad_u64_u32 v[66:67], s[28:29], v66, s22, 0
	v_add3_u32 v67, v67, v31, v29
	s_and_b64 s[28:29], s[30:31], exec
	v_lshl_add_u64 v[66:67], v[66:67], 1, v[32:33]
	s_cselect_b32 s48, 0x4000000, 64
	v_cvt_pk_bf16_f32 v18, v18, v19
	v_cvt_pk_bf16_f32 v19, v20, v21
	v_cvt_pk_bf16_f32 v20, v22, v23
	v_cvt_pk_bf16_f32 v21, v24, v25
	v_lshl_add_u64 v[22:23], v[66:67], 0, s[48:49]
	global_store_dwordx4 v[66:67], v[18:21], off nt
	s_nop 1
	v_cvt_pk_bf16_f32 v18, v82, v83
	v_cvt_pk_bf16_f32 v19, v84, v85
	v_cvt_pk_bf16_f32 v20, v86, v87
	v_cvt_pk_bf16_f32 v21, v88, v89
	global_store_dwordx4 v[22:23], v[18:21], off nt

.LBB0_396:
	v_lshl_add_u64 v[50:51], s[94:95], 0, v[50:51]
	v_mul_lo_u32 v29, v51, s22
	v_mul_lo_u32 v31, v50, s23
	v_mad_u64_u32 v[50:51], s[28:29], v50, s22, 0
	v_add3_u32 v51, v51, v31, v29
	s_and_b64 s[28:29], s[30:31], exec
	v_lshl_add_u64 v[50:51], v[50:51], 1, v[32:33]
	s_cselect_b32 s48, 0x4000000, 64
	v_cvt_pk_bf16_f32 v18, v18, v19
	v_cvt_pk_bf16_f32 v19, v20, v21
	v_cvt_pk_bf16_f32 v20, v22, v23
	v_cvt_pk_bf16_f32 v21, v24, v25
	v_lshl_add_u64 v[22:23], v[50:51], 0, s[48:49]
	global_store_dwordx4 v[50:51], v[18:21], off nt
	s_nop 1
	v_cvt_pk_bf16_f32 v18, v66, v67
	v_cvt_pk_bf16_f32 v19, v68, v69
	v_cvt_pk_bf16_f32 v20, v70, v71
	v_cvt_pk_bf16_f32 v21, v72, v73
	global_store_dwordx4 v[22:23], v[18:21], off nt

.LBB0_422:
	v_lshl_add_u64 v[2:3], s[94:95], 0, v[2:3]
	v_mul_lo_u32 v4, v3, s22
	v_mul_lo_u32 v5, v2, s23
	v_mad_u64_u32 v[2:3], s[4:5], v2, s22, 0
	v_add3_u32 v3, v3, v5, v4
	s_and_b64 s[4:5], s[30:31], exec
	v_lshl_add_u64 v[6:7], v[2:3], 1, v[32:33]
	s_cselect_b32 s48, 0x4000000, 64
	v_cvt_pk_bf16_f32 v2, v18, v19
	v_cvt_pk_bf16_f32 v3, v20, v21
	v_cvt_pk_bf16_f32 v4, v22, v23
	v_cvt_pk_bf16_f32 v5, v24, v25
	global_store_dwordx4 v[6:7], v[2:5], off nt
	v_lshl_add_u64 v[6:7], v[6:7], 0, s[48:49]
	s_nop 0
	v_cvt_pk_bf16_f32 v2, v50, v51
	v_cvt_pk_bf16_f32 v3, v52, v53
	v_cvt_pk_bf16_f32 v4, v54, v55
	v_cvt_pk_bf16_f32 v5, v56, v57
	global_store_dwordx4 v[6:7], v[2:5], off nt
	s_andn2_b64 vcc, exec, s[40:41]
	s_mov_b64 s[4:5], -1
	s_cbranch_vccnz .LBB0_176
	s_branch .LBB0_430

.Lsp_skip:
	s_lshl_b32 s0, s2, 3
	v_readlane_b32 s2, v253, 32
	s_add_i32 s2, s0, s2
	v_readlane_b32 s3, v253, 33
	s_branch .LBB0_706
.LBB0_677:
	s_cmp_eq_u32 s16, 0x7c
	s_cbranch_scc0 .Lsp_keep
	s_cmp_lt_u32 s2, 4
	s_cbranch_scc1 .Lsp_skip
	s_sub_i32 s2, s2, 4
	s_sub_i32 s16, s16, 4
